# phase 2 layer 1: loop-invariant mu_v quads loaded once for the A3 loop; v2t fragment loads issued before the t1 MFMA chain
# speedup vs baseline: 1.0171x; 1.0004x over previous
; DI unsigned pack2(float a, float b) { fv2 v = {a, b}; return __builtin_bit_cast(unsigned, __builtin_convertvector(v, bfv2)); }
; DI float bflo(unsigned u) { return __uint_as_float(u << 16); }
; DI float bfhi(unsigned u) { return __uint_as_float(u & 0xffff0000u); }
; DI void rwkv_prep(const Params& p, int l, int item, char* smraw) {
;     ...
;     for (int idx = tid; idx < 64 * 32; idx += 512) {
;       const int tok = idx >> 5, c8 = idx & 31;
;       const size_t m = (size_t)(T0 + tok);
;       const uint4 z = *(const uint4*)(SR + (tok + 1) * 776 + 512 + c8 * 8);
;       const uint4 zp = *(const uint4*)(SR + tok * 776 + 512 + c8 * 8);
;       const unsigned zz[4] = {z.x, z.y, z.z, z.w}, pp[4] = {zp.x, zp.y, zp.z, zp.w};
;       unsigned oo[4];
; #pragma unroll
;       for (int e = 0; e < 4; ++e) {
;         const float m0 = mu[512 + c8 * 8 + 2 * e], m1 = mu[512 + c8 * 8 + 2 * e + 1];
;         float x0 = bflo(zz[e]), x1 = bfhi(zz[e]);
;         x0 = x0 + (bflo(pp[e]) - x0) * m0; x1 = x1 + (bfhi(pp[e]) - x1) * m1;
;         oo[e] = pack2(x0, x1);
;       }
;       *(uint4*)(A3 + tok * 264 + c8 * 8) = make_uint4(oo[0], oo[1], oo[2], oo[3]);
;     }
.LBB0_387:
	s_or_b64 exec, exec, s[4:5]
	s_movk_i32 s0, 0x800
	v_cmp_gt_i32_e32 vcc, s0, v54
	s_and_b64 s[6:7], s[8:9], vcc
	s_waitcnt lgkmcnt(0)
	s_barrier
	s_and_saveexec_b64 s[4:5], s[6:7]
	s_movk_i32 s1, 0x610
	s_cbranch_execz .LBB0_390
	v_lshlrev_b32_e32 v0, 3, v54
	v_and_b32_e32 v136, 0xf8, v0
	v_lshlrev_b32_e32 v136, 2, v136
	global_load_dwordx4 v[128:131], v136, s[38:39] offset:2064
	global_load_dwordx4 v[132:135], v136, s[38:39] offset:2048
	s_mov_b64 s[36:37], 0
	s_waitcnt vmcnt(0)
	v_mov_b32_e32 v2, v54
.LBB0_389:
	v_ashrrev_i32_e32 v3, 5, v2
	v_and_b32_e32 v12, 0xf8, v0
	v_mul_lo_u32 v4, v3, s1
	v_lshlrev_b32_e32 v24, 1, v12
	v_add3_u32 v8, 0, v4, v24
	v_lshlrev_b32_e32 v16, 2, v12
	ds_read_b128 v[4:7], v8 offset:54800
	ds_read_b128 v[8:11], v8 offset:53248
	s_nop 0
	s_movk_i32 s0, 0x210
	v_mul_lo_u32 v3, v3, s0
	s_waitcnt lgkmcnt(1)
	v_lshlrev_b32_e32 v20, 16, v4
	v_and_b32_e32 v21, 0xffff0000, v4
	s_waitcnt lgkmcnt(0)
	v_lshlrev_b32_e32 v22, 16, v8
	v_and_b32_e32 v23, 0xffff0000, v8
	v_pk_add_f32 v[22:23], v[22:23], v[20:21] neg_lo:[0,1] neg_hi:[0,1]
	v_lshlrev_b32_e32 v8, 16, v9
	v_and_b32_e32 v9, 0xffff0000, v9
	v_add3_u32 v3, 0, v3, v24
	s_movk_i32 s0, 0x5ff
	v_cmp_lt_i32_e32 vcc, s0, v2
	v_add_u32_e32 v0, 0x1000, v0
	s_or_b64 s[36:37], vcc, s[36:37]
	s_waitcnt vmcnt(0)
	v_pk_fma_f32 v[16:17], v[22:23], v[132:133], v[20:21]
	s_nop 0
	v_cvt_pk_bf16_f32 v4, v16, v17
	v_lshlrev_b32_e32 v16, 16, v5
	v_and_b32_e32 v17, 0xffff0000, v5
	v_pk_add_f32 v[8:9], v[8:9], v[16:17] neg_lo:[0,1] neg_hi:[0,1]
	s_nop 0
	v_pk_fma_f32 v[8:9], v[8:9], v[134:135], v[16:17]
	v_lshlrev_b32_e32 v16, 16, v10
	v_cvt_pk_bf16_f32 v5, v8, v9
	v_lshlrev_b32_e32 v8, 16, v6
	v_and_b32_e32 v9, 0xffff0000, v6
	v_and_b32_e32 v17, 0xffff0000, v10
	v_pk_add_f32 v[16:17], v[16:17], v[8:9] neg_lo:[0,1] neg_hi:[0,1]
	v_lshlrev_b32_e32 v10, 16, v11
	v_pk_fma_f32 v[8:9], v[16:17], v[128:129], v[8:9]
	v_and_b32_e32 v11, 0xffff0000, v11
	v_cvt_pk_bf16_f32 v6, v8, v9
	v_lshlrev_b32_e32 v8, 16, v7
	v_and_b32_e32 v9, 0xffff0000, v7
	v_pk_add_f32 v[10:11], v[10:11], v[8:9] neg_lo:[0,1] neg_hi:[0,1]
	s_nop 0
	v_pk_fma_f32 v[8:9], v[10:11], v[130:131], v[8:9]
	s_nop 0
	v_cvt_pk_bf16_f32 v7, v8, v9
	ds_write_b128 v3, v[4:7] offset:18432
	v_add_u32_e32 v3, 0x200, v2
	v_mov_b32_e32 v2, v3
	s_andn2_b64 exec, exec, s[36:37]
	s_cbranch_execnz .LBB0_389

; #define MFMA32(a, b, c) __builtin_amdgcn_mfma_f32_32x32x16_bf16((a), (b), (c), 0, 0, 0)
; DI unsigned pack2(float a, float b) { fv2 v = {a, b}; return __builtin_bit_cast(unsigned, __builtin_convertvector(v, bfv2)); }
; DI void rwkv_prep(const Params& p, int l, int item, char* smraw) {
;     ...
; #pragma unroll
;       for (int s = 0; s < 4; ++s) {
;         const bf16x8 f1 = *(const bf16x8*)(A1 + (32 * tt + r31) * LDT + 16 * s + 8 * h);
;         const bf16x8 f2 = *(const bf16x8*)(A2 + (32 * tt + r31) * LDT + 16 * s + 8 * h);
;         const bf16x8 gw = *(const bf16x8*)(lw2 + (w * 64 + 32 * nt + r31) * 64 + 16 * s + 8 * h);
;         const bf16x8 ga = *(const bf16x8*)(la2 + (w * 64 + 32 * nt + r31) * 64 + 16 * s + 8 * h);
;         aw = MFMA32(gw, f1, aw);
;         aa = MFMA32(ga, f2, aa);
;       }
;       if (l == 1) {
;         f32x16 t1;
; #pragma unroll
;         for (int e = 0; e < 16; ++e) t1[e] = 0.f;
; #pragma unroll
;         for (int s = 0; s < 16; ++s) {
;           const bf16x8 fv = *(const bf16x8*)(A3 + (32 * tt + r31) * 264 + 16 * s + 8 * h);
;           const bf16x8 g1 = *(const bf16x8*)(v1t + r31 * 256 + 16 * s + 8 * h);
;           t1 = MFMA32(g1, fv, t1);
;         }
; #pragma unroll
;         for (int s = 0; s < 2; ++s) {
;           unsigned pk[4];
; #pragma unroll
;           for (int e = 0; e < 4; ++e) pk[e] = pack2(t1[8 * s + 2 * e], t1[8 * s + 2 * e + 1]);
;           const bf16x8 fb = __builtin_bit_cast(bf16x8, make_uint4(pk[0], pk[1], pk[2], pk[3]));
;           const bf16_t* vr = v2t + (w * 64 + 32 * nt + r31) * 32 + 16 * s + 4 * h;
;           const uint2 lo = *(const uint2*)vr; const uint2 hi = *(const uint2*)(vr + 8);
;           const bf16x8 fa = __builtin_bit_cast(bf16x8, make_uint4(lo.x, lo.y, hi.x, hi.y));
;           av = MFMA32(fa, fb, av);
;         }
.Lp2_nog:
	ds_read_b128 v[18:21], v86 offset:9216
	global_load_dwordx4 v[2:5], v[50:51], off
	global_load_dwordx4 v[22:25], v[52:53], off
	ds_read_b128 v[6:9], v86
	ds_read_b128 v[34:37], v86 offset:32
	ds_read_b128 v[38:41], v86 offset:9248
	global_load_dwordx4 v[42:45], v[50:51], off offset:32
	global_load_dwordx4 v[46:49], v[52:53], off offset:32
	global_load_dwordx4 v[192:195], v[50:51], off offset:64
	global_load_dwordx4 v[196:199], v[52:53], off offset:64
	global_load_dwordx4 v[210:213], v[50:51], off offset:96
	global_load_dwordx4 v[214:217], v[52:53], off offset:96
	s_and_b64 vcc, exec, s[8:9]
	s_waitcnt vmcnt(7) lgkmcnt(2)
	v_mfma_f32_32x32x16_bf16 v[2:17], v[2:5], v[6:9], 0
	s_waitcnt vmcnt(6)
	v_mfma_f32_32x32x16_bf16 v[18:33], v[22:25], v[18:21], 0
	s_waitcnt vmcnt(5) lgkmcnt(1)
	v_mfma_f32_32x32x16_bf16 v[2:17], v[42:45], v[34:37], v[2:17]
	s_waitcnt vmcnt(4) lgkmcnt(0)
	v_mfma_f32_32x32x16_bf16 v[18:33], v[46:49], v[38:41], v[18:33]
	ds_read_b128 v[34:37], v86 offset:64
	ds_read_b128 v[38:41], v86 offset:9280
	s_waitcnt vmcnt(3) lgkmcnt(1)
	v_mfma_f32_32x32x16_bf16 v[2:17], v[192:195], v[34:37], v[2:17]
	s_waitcnt vmcnt(2) lgkmcnt(0)
	v_mfma_f32_32x32x16_bf16 v[18:33], v[196:199], v[38:41], v[18:33]
	ds_read_b128 v[34:37], v86 offset:96
	ds_read_b128 v[38:41], v86 offset:9312
	s_waitcnt vmcnt(1) lgkmcnt(1)
	v_mfma_f32_32x32x16_bf16 v[2:17], v[210:213], v[34:37], v[2:17]
	v_mov_b32_e32 v34, 0
	v_mov_b32_e32 v35, 0
	v_mov_b32_e32 v36, 0
	v_mov_b32_e32 v37, 0
	v_mov_b32_e32 v42, 0
	v_mov_b32_e32 v43, 0
	v_mov_b32_e32 v44, 0
	s_waitcnt vmcnt(0) lgkmcnt(0)
	v_mfma_f32_32x32x16_bf16 v[18:33], v[214:217], v[38:41], v[18:33]
	v_mov_b32_e32 v38, 0
	v_mov_b32_e32 v39, 0
	v_mov_b32_e32 v40, 0
	v_mov_b32_e32 v41, 0
	v_mov_b32_e32 v45, 0
	v_mov_b32_e32 v46, 0
	v_mov_b32_e32 v47, 0
	v_mov_b32_e32 v48, 0
	v_mov_b32_e32 v49, 0
	s_cbranch_vccz .LBB0_394
	v_lshl_or_b32 v248, s4, 11, v124
	v_mov_b32_e32 v249, 0
	v_lshl_add_u64 v[248:249], v[100:101], 0, v[248:249]
	global_load_dwordx2 v[240:241], v[248:249], off
	global_load_dwordx2 v[242:243], v[248:249], off offset:16
	global_load_dwordx2 v[244:245], v[248:249], off offset:32
	global_load_dwordx2 v[246:247], v[248:249], off offset:48
	ds_read_b128 v[38:41], v96 offset:18432
	ds_read_b128 v[58:61], v96 offset:18464
	v_lshl_or_b32 v0, s4, 11, v124
	ds_read_b128 v[34:37], v96 offset:18496
	s_waitcnt lgkmcnt(2)
	v_mfma_f32_32x32x16_bf16 v[42:57], v[128:131], v[38:41], 0
	ds_read_b128 v[38:41], v96 offset:18528
	s_waitcnt lgkmcnt(1)
	v_mfma_f32_32x32x16_bf16 v[42:57], v[132:135], v[58:61], v[42:57]
	v_lshl_add_u64 v[58:59], v[100:101], 0, v[0:1]
	s_waitcnt lgkmcnt(1)
	v_mfma_f32_32x32x16_bf16 v[42:57], v[136:139], v[34:37], v[42:57]
	ds_read_b128 v[34:37], v96 offset:18560
	s_waitcnt lgkmcnt(1)
	v_mfma_f32_32x32x16_bf16 v[42:57], v[140:143], v[38:41], v[42:57]
	ds_read_b128 v[38:41], v96 offset:18592
	s_waitcnt lgkmcnt(1)
	v_mfma_f32_32x32x16_bf16 v[42:57], v[144:147], v[34:37], v[42:57]
	ds_read_b128 v[34:37], v96 offset:18624
	s_waitcnt lgkmcnt(1)
	v_mfma_f32_32x32x16_bf16 v[42:57], v[148:151], v[38:41], v[42:57]
	ds_read_b128 v[38:41], v96 offset:18656
	s_waitcnt lgkmcnt(1)
	v_mfma_f32_32x32x16_bf16 v[42:57], v[152:155], v[34:37], v[42:57]
	ds_read_b128 v[34:37], v96 offset:18688
	s_waitcnt lgkmcnt(1)
	v_mfma_f32_32x32x16_bf16 v[42:57], v[156:159], v[38:41], v[42:57]
	ds_read_b128 v[38:41], v96 offset:18720
	s_waitcnt lgkmcnt(1)
	v_mfma_f32_32x32x16_bf16 v[42:57], v[160:163], v[34:37], v[42:57]
	ds_read_b128 v[34:37], v96 offset:18752
	s_waitcnt lgkmcnt(1)
	v_mfma_f32_32x32x16_bf16 v[42:57], v[164:167], v[38:41], v[42:57]
	ds_read_b128 v[38:41], v96 offset:18784
	s_waitcnt lgkmcnt(1)
	v_mfma_f32_32x32x16_bf16 v[42:57], v[168:171], v[34:37], v[42:57]
	ds_read_b128 v[34:37], v96 offset:18816
	s_waitcnt lgkmcnt(1)
	v_mfma_f32_32x32x16_bf16 v[42:57], v[172:175], v[38:41], v[42:57]
	ds_read_b128 v[38:41], v96 offset:18848
	s_waitcnt lgkmcnt(1)
	v_mfma_f32_32x32x16_bf16 v[42:57], v[176:179], v[34:37], v[42:57]
	ds_read_b128 v[34:37], v96 offset:18880
	s_waitcnt lgkmcnt(1)
	v_mfma_f32_32x32x16_bf16 v[42:57], v[180:183], v[38:41], v[42:57]
	ds_read_b128 v[38:41], v96 offset:18912
	s_waitcnt lgkmcnt(1)
	v_mfma_f32_32x32x16_bf16 v[42:57], v[184:187], v[34:37], v[42:57]
	s_waitcnt lgkmcnt(0)
	v_mfma_f32_32x32x16_bf16 v[42:57], v[188:191], v[38:41], v[42:57]
	s_nop 9
	v_cvt_pk_bf16_f32 v50, v50, v51
	v_cvt_pk_bf16_f32 v51, v52, v53
	v_cvt_pk_bf16_f32 v52, v54, v55
	v_cvt_pk_bf16_f32 v53, v56, v57
	v_cvt_pk_bf16_f32 v34, v42, v43
	v_cvt_pk_bf16_f32 v35, v44, v45
	v_cvt_pk_bf16_f32 v36, v46, v47
	v_cvt_pk_bf16_f32 v37, v48, v49
	s_waitcnt vmcnt(0)
	s_nop 0
	v_mfma_f32_32x32x16_bf16 v[34:49], v[240:243], v[34:37], 0
	v_mfma_f32_32x32x16_bf16 v[34:49], v[244:247], v[50:53], v[34:49]
